# next-tile index: row-group size is always 8 where nM = 256, generic reciprocal division replaced by shift and mask (4 GEMM phase types)
# speedup vs baseline: 1.0060x; 1.0007x over previous
;     __device__ bool next(int i, Unit& u) const {
;         const long L = (long)i * G + c; if (L >= nwg) return false;
;         int wgid = (int)L; { const int q = nwg / NXCD, r = nwg % NXCD, xcd = wgid % NXCD, off = wgid / NXCD; wgid = (xcd < r ? xcd * (q + 1) : r * (q + 1) + (xcd - r) * q) + off; }
;         const int nig = WGM * nN, gid = wgid / nig, fm = gid * WGM, gsz = (nM - fm) < WGM ? (nM - fm) : WGM;
;         u.pm = fm + ((wgid % nig) % gsz); u.pn = (wgid % nig) / gsz; return true;
;     }
.LBB0_291:
	s_add_i32 s57, s57, 1
	s_mul_i32 s7, s57, s25
	s_mul_hi_u32 s21, s57, s24
	s_add_i32 s21, s21, s7
	s_mul_i32 s7, s57, s24
	s_add_u32 s42, s7, s2
	s_addc_u32 s43, s21, s3
	v_mov_b64_e32 v[2:3], s[36:37]
	v_cmp_ge_i64_e32 vcc, s[42:43], v[2:3]
	v_cmp_lt_i64_e64 s[40:41], s[42:43], v[2:3]
	s_cbranch_vccnz .LBB0_293
	s_ashr_i32 s7, s42, 31
	s_lshr_b32 s7, s7, 29
	s_add_i32 s7, s42, s7
	s_ashr_i32 s20, s7, 3
	s_and_b32 s7, s7, -8
	s_sub_i32 s7, s42, s7
	s_lshr_b32 s21, s7, 31
	s_or_b32 s21, s21, s30
	s_mul_i32 s7, s21, s7
	s_add_i32 s7, s7, s20
	s_abs_i32 s21, s7
	s_mul_hi_u32 s22, s21, s38
	s_mul_i32 s23, s22, s9
	s_ashr_i32 s20, s7, 31
	s_sub_i32 s21, s21, s23
	s_xor_b32 s20, s20, s31
	s_add_i32 s23, s22, 1
	s_sub_i32 s42, s21, s9
	s_cmp_ge_u32 s21, s9
	s_cselect_b32 s22, s23, s22
	s_cselect_b32 s21, s42, s21
	s_add_i32 s23, s22, 1
	s_cmp_ge_u32 s21, s9
	s_cselect_b32 s21, s23, s22
	s_xor_b32 s21, s21, s20
	s_sub_i32 s20, s21, s20
	s_lshl_b32 s21, s20, 3
	s_sub_i32 s22, 0x100, s21
	s_min_i32 s22, s22, 8
	s_mul_i32 s20, s20, s8
	s_sub_i32 s7, s7, s20
	s_lshr_b32 s20, s7, 3
	s_and_b32 s7, s7, 7
	s_add_i32 s22, s7, s21

;     __device__ bool next(int i, Unit& u) const {
;         const long L = (long)i * G + c; if (L >= nwg) return false;
;         int wgid = (int)L; { const int q = nwg / NXCD, r = nwg % NXCD, xcd = wgid % NXCD, off = wgid / NXCD; wgid = (xcd < r ? xcd * (q + 1) : r * (q + 1) + (xcd - r) * q) + off; }
;         const int nig = WGM * nN, gid = wgid / nig, fm = gid * WGM, gsz = (nM - fm) < WGM ? (nM - fm) : WGM;
;         u.pm = fm + ((wgid % nig) % gsz); u.pn = (wgid % nig) / gsz; return true;
;     }
.LBB0_704:
	s_ashr_i32 s16, s18, 3
	s_add_i32 s16, s20, s16
	s_ashr_i32 s17, s16, 31
	s_lshr_b32 s17, s17, 27
	s_add_i32 s17, s16, s17
	s_ashr_i32 s18, s17, 5
	s_lshl_b32 s18, s18, 3
	s_sub_i32 s19, 0x100, s18
	s_min_i32 s19, s19, 8
	s_andn2_b32 s17, s17, 31
	s_sub_i32 s17, s16, s17
	s_lshr_b32 s16, s17, 3
	s_and_b32 s17, s17, 7
	s_add_i32 s18, s18, s17

;     __device__ bool next(int i, Unit& u) const {
;         const long L = (long)i * G + c; if (L >= nwg) return false;
;         int wgid = (int)L; { const int q = nwg / NXCD, r = nwg % NXCD, xcd = wgid % NXCD, off = wgid / NXCD; wgid = (xcd < r ? xcd * (q + 1) : r * (q + 1) + (xcd - r) * q) + off; }
;         const int nig = WGM * nN, gid = wgid / nig, fm = gid * WGM, gsz = (nM - fm) < WGM ? (nM - fm) : WGM;
;         u.pm = fm + ((wgid % nig) % gsz); u.pn = (wgid % nig) / gsz; return true;
;     }
.LBB0_952:
	s_ashr_i32 s16, s22, 3
	s_add_i32 s16, s44, s16
	s_ashr_i32 s17, s16, 31
	s_lshr_b32 s17, s17, 27
	s_add_i32 s17, s16, s17
	s_ashr_i32 s22, s17, 5
	s_lshl_b32 s22, s22, 3
	s_sub_i32 s23, 0x100, s22
	s_min_i32 s23, s23, 8
	s_andn2_b32 s17, s17, 31
	s_sub_i32 s16, s16, s17
	s_lshr_b32 s50, s16, 3
	s_and_b32 s16, s16, 7
	s_add_i32 s51, s22, s16

;     __device__ bool next(int i, Unit& u) const {
;         const long L = (long)i * G + c; if (L >= nwg) return false;
;         int wgid = (int)L; { const int q = nwg / NXCD, r = nwg % NXCD, xcd = wgid % NXCD, off = wgid / NXCD; wgid = (xcd < r ? xcd * (q + 1) : r * (q + 1) + (xcd - r) * q) + off; }
;         const int nig = WGM * nN, gid = wgid / nig, fm = gid * WGM, gsz = (nM - fm) < WGM ? (nM - fm) : WGM;
;         u.pm = fm + ((wgid % nig) % gsz); u.pn = (wgid % nig) / gsz; return true;
;     }
.LBB0_1053:
	s_add_i32 s52, s52, 1
	s_mul_i32 s6, s52, s25
	s_mul_hi_u32 s7, s52, s24
	s_add_i32 s7, s7, s6
	s_mul_i32 s6, s52, s24
	s_add_u32 s6, s6, s2
	s_addc_u32 s7, s7, s3
	v_mov_b64_e32 v[2:3], s[36:37]
	v_cmp_ge_i64_e32 vcc, s[6:7], v[2:3]
	v_cmp_lt_i64_e64 s[40:41], s[6:7], v[2:3]
	s_cbranch_vccnz .LBB0_1055
	s_ashr_i32 s7, s6, 31
	s_lshr_b32 s7, s7, 29
	s_add_i32 s7, s6, s7
	s_ashr_i32 s18, s7, 3
	s_and_b32 s7, s7, -8
	s_sub_i32 s6, s6, s7
	s_lshr_b32 s7, s6, 31
	s_or_b32 s7, s7, s44
	s_mul_i32 s6, s7, s6
	s_add_i32 s6, s6, s18
	s_abs_i32 s18, s6
	s_mul_hi_u32 s19, s18, s46
	s_mul_i32 s20, s19, s45
	s_sub_i32 s18, s18, s20
	s_ashr_i32 s7, s6, 31
	s_add_i32 s20, s19, 1
	s_sub_i32 s21, s18, s45
	s_cmp_ge_u32 s18, s45
	s_cselect_b32 s19, s20, s19
	s_cselect_b32 s18, s21, s18
	s_add_i32 s20, s19, 1
	s_cmp_ge_u32 s18, s45
	s_cselect_b32 s18, s20, s19
	s_xor_b32 s18, s18, s7
	s_sub_i32 s7, s18, s7
	s_lshl_b32 s18, s7, 3
	s_sub_i32 s19, 0x100, s18
	s_min_i32 s19, s19, 8
	s_mul_i32 s7, s7, s45
	s_sub_i32 s6, s6, s7
	s_lshr_b32 s59, s6, 3
	s_and_b32 s6, s6, 7
	s_add_i32 s60, s6, s18
